# on top of v7: out-projection residual epilogue issues all 16 residual-stream loads of the tile up front with counted waits instead of load-wait per row segment
# speedup vs baseline: 1.0019x; 1.0019x over previous
; #define GAS __attribute__((address_space(1)))
;     __device__ __forceinline__ void operator()(const pg8::f32x4 (&acc)[2][2][4][2], const pg8::Unit& u, int wr, int wc, int fr, int fq) const {
;         const int row0 = u.pm * 256 + wr * 64 + fr, col0 = u.pn * 256 + wc * 32 + 8 * fq;
; #pragma unroll
;         for (int ai = 0; ai < 2; ++ai)
; #pragma unroll
;             for (int m = 0; m < 4; ++m) { const int row = row0 + ai * 128 + m * 16; const size_t off = (size_t)row * D + col0; float ss = 0.f;
; #pragma unroll
;                 for (int bj = 0; bj < 2; ++bj) { const size_t o = off + bj * 128; pg8::f32x4 b0, b1;
;                     if (first) { b0 = *(const GAS pg8::f32x4*)(base32 + o); b1 = *(const GAS pg8::f32x4*)(base32 + o + 4); }
;                     else { const v4u w = *(const GAS v4u*)(xres + o);
;                         b0 = (pg8::f32x4){__uint_as_float(w.x << 16), __uint_as_float(w.x & 0xffff0000u), __uint_as_float(w.y << 16), __uint_as_float(w.y & 0xffff0000u)};
;                         b1 = (pg8::f32x4){__uint_as_float(w.z << 16), __uint_as_float(w.z & 0xffff0000u), __uint_as_float(w.w << 16), __uint_as_float(w.w & 0xffff0000u)}; }
.LBB0_479:
	v_lshl_add_u32 v152, s38, 8, v139
	v_lshl_or_b32 v150, s8, 8, v161
	v_ashrrev_i32_e32 v153, 31, v152
	v_ashrrev_i32_e32 v151, 31, v150
	v_lshlrev_b64 v[130:131], 10, v[152:153]
	v_lshl_add_u64 v[158:159], v[130:131], 0, v[150:151]
	s_and_b64 vcc, exec, s[22:23]
	v_lshl_add_u64 v[154:155], v[158:159], 1, s[16:17]
	s_cbranch_vccz .LBB0_634
	global_load_dwordx4 v[166:169], v[154:155], off
	global_load_dwordx4 v[170:173], v[154:155], off offset:256
	v_add_co_u32_e32 v234, vcc, 0x8000, v154
	s_nop 1
	v_addc_co_u32_e32 v235, vcc, 0, v155, vcc
	global_load_dwordx4 v[174:177], v[234:235], off
	global_load_dwordx4 v[178:181], v[234:235], off offset:256
	v_add_co_u32_e32 v234, vcc, 0x10000, v154
	s_nop 1
	v_addc_co_u32_e32 v235, vcc, 0, v155, vcc
	global_load_dwordx4 v[182:185], v[234:235], off
	global_load_dwordx4 v[194:197], v[234:235], off offset:256
	v_add_co_u32_e32 v234, vcc, 0x18000, v154
	s_nop 1
	v_addc_co_u32_e32 v235, vcc, 0, v155, vcc
	global_load_dwordx4 v[198:201], v[234:235], off
	global_load_dwordx4 v[202:205], v[234:235], off offset:256
	v_add_co_u32_e32 v234, vcc, 0x40000, v154
	s_nop 1
	v_addc_co_u32_e32 v235, vcc, 0, v155, vcc
	global_load_dwordx4 v[206:209], v[234:235], off
	global_load_dwordx4 v[210:213], v[234:235], off offset:256
	v_add_co_u32_e32 v234, vcc, 0x48000, v154
	s_nop 1
	v_addc_co_u32_e32 v235, vcc, 0, v155, vcc
	global_load_dwordx4 v[214:217], v[234:235], off
	global_load_dwordx4 v[218:221], v[234:235], off offset:256
	v_add_co_u32_e32 v234, vcc, 0x50000, v154
	s_nop 1
	v_addc_co_u32_e32 v235, vcc, 0, v155, vcc
	global_load_dwordx4 v[222:225], v[234:235], off
	global_load_dwordx4 v[226:229], v[234:235], off offset:256
	v_add_co_u32_e32 v234, vcc, 0x58000, v154
	s_nop 1
	v_addc_co_u32_e32 v235, vcc, 0, v155, vcc
	global_load_dwordx4 v[230:233], v[234:235], off
	global_load_dwordx4 v[140:143], v[234:235], off offset:256
	s_waitcnt vmcnt(15)
	v_mov_b32_e32 v130, v166
	v_mov_b32_e32 v131, v167
	v_mov_b32_e32 v132, v168
	v_mov_b32_e32 v133, v169
	v_lshlrev_b32_e32 v134, 16, v130
	v_and_b32_e32 v135, 0xffff0000, v130
	v_lshlrev_b32_e32 v136, 16, v131
	v_and_b32_e32 v137, 0xffff0000, v131
	v_lshlrev_b32_e32 v130, 16, v132
	v_and_b32_e32 v131, 0xffff0000, v132
	v_lshlrev_b32_e32 v132, 16, v133
	v_and_b32_e32 v133, 0xffff0000, v133
	v_lshl_add_u64 v[156:157], v[158:159], 2, s[14:15]
	s_cbranch_execnz .LBB0_482

; #define GAS __attribute__((address_space(1)))
;     __device__ __forceinline__ void operator()(const pg8::f32x4 (&acc)[2][2][4][2], const pg8::Unit& u, int wr, int wc, int fr, int fq) const {
;     ...
;                 for (int bj = 0; bj < 2; ++bj) { const size_t o = off + bj * 128; pg8::f32x4 b0, b1;
;                     if (first) { b0 = *(const GAS pg8::f32x4*)(base32 + o); b1 = *(const GAS pg8::f32x4*)(base32 + o + 4); }
;                     else { const v4u w = *(const GAS v4u*)(xres + o);
;                         b0 = (pg8::f32x4){__uint_as_float(w.x << 16), __uint_as_float(w.x & 0xffff0000u), __uint_as_float(w.y << 16), __uint_as_float(w.y & 0xffff0000u)};
;                         b1 = (pg8::f32x4){__uint_as_float(w.z << 16), __uint_as_float(w.z & 0xffff0000u), __uint_as_float(w.w << 16), __uint_as_float(w.w & 0xffff0000u)}; }
.LBB0_485:
	s_waitcnt vmcnt(14)
	v_mov_b32_e32 v122, v170
	v_mov_b32_e32 v123, v171
	v_mov_b32_e32 v124, v172
	v_mov_b32_e32 v125, v173
	v_lshlrev_b32_e32 v126, 16, v122
	v_and_b32_e32 v127, 0xffff0000, v122
	v_lshlrev_b32_e32 v128, 16, v123
	v_and_b32_e32 v129, 0xffff0000, v123
	v_lshlrev_b32_e32 v122, 16, v124
	v_and_b32_e32 v123, 0xffff0000, v124
	v_lshlrev_b32_e32 v124, 16, v125
	v_and_b32_e32 v125, 0xffff0000, v125
	s_cbranch_execnz .LBB0_487

; #define GAS __attribute__((address_space(1)))
;     __device__ __forceinline__ void operator()(const pg8::f32x4 (&acc)[2][2][4][2], const pg8::Unit& u, int wr, int wc, int fr, int fq) const {
;     ...
;                 for (int bj = 0; bj < 2; ++bj) { const size_t o = off + bj * 128; pg8::f32x4 b0, b1;
;                     if (first) { b0 = *(const GAS pg8::f32x4*)(base32 + o); b1 = *(const GAS pg8::f32x4*)(base32 + o + 4); }
;                     else { const v4u w = *(const GAS v4u*)(xres + o);
;                         b0 = (pg8::f32x4){__uint_as_float(w.x << 16), __uint_as_float(w.x & 0xffff0000u), __uint_as_float(w.y << 16), __uint_as_float(w.y & 0xffff0000u)};
;                         b1 = (pg8::f32x4){__uint_as_float(w.z << 16), __uint_as_float(w.z & 0xffff0000u), __uint_as_float(w.w << 16), __uint_as_float(w.w & 0xffff0000u)}; }
.LBB0_495:
	v_or_b32_e32 v122, 16, v152
	v_ashrrev_i32_e32 v123, 31, v122
	s_waitcnt lgkmcnt(0)
	v_lshlrev_b64 v[114:115], 10, v[122:123]
	v_lshl_add_u64 v[128:129], v[114:115], 0, v[150:151]
	s_and_b64 vcc, exec, s[22:23]
	v_lshl_add_u64 v[124:125], v[128:129], 1, s[16:17]
	s_cbranch_vccz .LBB0_635
	s_waitcnt vmcnt(13)
	v_mov_b32_e32 v114, v174
	v_mov_b32_e32 v115, v175
	v_mov_b32_e32 v116, v176
	v_mov_b32_e32 v117, v177
	v_lshlrev_b32_e32 v118, 16, v114
	v_and_b32_e32 v119, 0xffff0000, v114
	v_lshlrev_b32_e32 v120, 16, v115
	v_and_b32_e32 v121, 0xffff0000, v115
	v_lshlrev_b32_e32 v114, 16, v116
	v_and_b32_e32 v115, 0xffff0000, v116
	v_lshlrev_b32_e32 v116, 16, v117
	v_and_b32_e32 v117, 0xffff0000, v117
	v_lshl_add_u64 v[126:127], v[128:129], 2, s[14:15]
	s_cbranch_execnz .LBB0_498

; #define GAS __attribute__((address_space(1)))
;     __device__ __forceinline__ void operator()(const pg8::f32x4 (&acc)[2][2][4][2], const pg8::Unit& u, int wr, int wc, int fr, int fq) const {
;     ...
;                 for (int bj = 0; bj < 2; ++bj) { const size_t o = off + bj * 128; pg8::f32x4 b0, b1;
;                     if (first) { b0 = *(const GAS pg8::f32x4*)(base32 + o); b1 = *(const GAS pg8::f32x4*)(base32 + o + 4); }
;                     else { const v4u w = *(const GAS v4u*)(xres + o);
;                         b0 = (pg8::f32x4){__uint_as_float(w.x << 16), __uint_as_float(w.x & 0xffff0000u), __uint_as_float(w.y << 16), __uint_as_float(w.y & 0xffff0000u)};
;                         b1 = (pg8::f32x4){__uint_as_float(w.z << 16), __uint_as_float(w.z & 0xffff0000u), __uint_as_float(w.w << 16), __uint_as_float(w.w & 0xffff0000u)}; }
.LBB0_501:
	s_waitcnt vmcnt(12)
	v_mov_b32_e32 v104, v178
	v_mov_b32_e32 v105, v179
	v_mov_b32_e32 v106, v180
	v_mov_b32_e32 v107, v181
	v_lshlrev_b32_e32 v108, 16, v104
	v_and_b32_e32 v109, 0xffff0000, v104
	v_lshlrev_b32_e32 v110, 16, v105
	v_and_b32_e32 v111, 0xffff0000, v105
	v_lshlrev_b32_e32 v104, 16, v106
	v_and_b32_e32 v105, 0xffff0000, v106
	v_lshlrev_b32_e32 v106, 16, v107
	v_and_b32_e32 v107, 0xffff0000, v107
	s_cbranch_execnz .LBB0_503

; #define GAS __attribute__((address_space(1)))
;     __device__ __forceinline__ void operator()(const pg8::f32x4 (&acc)[2][2][4][2], const pg8::Unit& u, int wr, int wc, int fr, int fq) const {
;     ...
;                 for (int bj = 0; bj < 2; ++bj) { const size_t o = off + bj * 128; pg8::f32x4 b0, b1;
;                     if (first) { b0 = *(const GAS pg8::f32x4*)(base32 + o); b1 = *(const GAS pg8::f32x4*)(base32 + o + 4); }
;                     else { const v4u w = *(const GAS v4u*)(xres + o);
;                         b0 = (pg8::f32x4){__uint_as_float(w.x << 16), __uint_as_float(w.x & 0xffff0000u), __uint_as_float(w.y << 16), __uint_as_float(w.y & 0xffff0000u)};
;                         b1 = (pg8::f32x4){__uint_as_float(w.z << 16), __uint_as_float(w.z & 0xffff0000u), __uint_as_float(w.w << 16), __uint_as_float(w.w & 0xffff0000u)}; }
.LBB0_517:
	v_or_b32_e32 v104, 32, v152
	v_ashrrev_i32_e32 v105, 31, v104
	s_waitcnt lgkmcnt(0)
	v_lshlrev_b64 v[96:97], 10, v[104:105]
	v_lshl_add_u64 v[110:111], v[96:97], 0, v[150:151]
	s_and_b64 vcc, exec, s[22:23]
	v_lshl_add_u64 v[106:107], v[110:111], 1, s[16:17]
	s_cbranch_vccz .LBB0_636
	s_waitcnt vmcnt(11)
	v_mov_b32_e32 v96, v182
	v_mov_b32_e32 v97, v183
	v_mov_b32_e32 v98, v184
	v_mov_b32_e32 v99, v185
	v_lshlrev_b32_e32 v100, 16, v96
	v_and_b32_e32 v101, 0xffff0000, v96
	v_lshlrev_b32_e32 v102, 16, v97
	v_and_b32_e32 v103, 0xffff0000, v97
	v_lshlrev_b32_e32 v96, 16, v98
	v_and_b32_e32 v97, 0xffff0000, v98
	v_lshlrev_b32_e32 v98, 16, v99
	v_and_b32_e32 v99, 0xffff0000, v99
	v_lshl_add_u64 v[108:109], v[110:111], 2, s[14:15]
	s_cbranch_execnz .LBB0_520

; #define GAS __attribute__((address_space(1)))
;     __device__ __forceinline__ void operator()(const pg8::f32x4 (&acc)[2][2][4][2], const pg8::Unit& u, int wr, int wc, int fr, int fq) const {
;     ...
;                 for (int bj = 0; bj < 2; ++bj) { const size_t o = off + bj * 128; pg8::f32x4 b0, b1;
;                     if (first) { b0 = *(const GAS pg8::f32x4*)(base32 + o); b1 = *(const GAS pg8::f32x4*)(base32 + o + 4); }
;                     else { const v4u w = *(const GAS v4u*)(xres + o);
;                         b0 = (pg8::f32x4){__uint_as_float(w.x << 16), __uint_as_float(w.x & 0xffff0000u), __uint_as_float(w.y << 16), __uint_as_float(w.y & 0xffff0000u)};
;                         b1 = (pg8::f32x4){__uint_as_float(w.z << 16), __uint_as_float(w.z & 0xffff0000u), __uint_as_float(w.w << 16), __uint_as_float(w.w & 0xffff0000u)}; }
.LBB0_523:
	s_waitcnt vmcnt(10)
	v_mov_b32_e32 v88, v194
	v_mov_b32_e32 v89, v195
	v_mov_b32_e32 v90, v196
	v_mov_b32_e32 v91, v197
	v_lshlrev_b32_e32 v92, 16, v88
	v_and_b32_e32 v93, 0xffff0000, v88
	v_lshlrev_b32_e32 v94, 16, v89
	v_and_b32_e32 v95, 0xffff0000, v89
	v_lshlrev_b32_e32 v88, 16, v90
	v_and_b32_e32 v89, 0xffff0000, v90
	v_lshlrev_b32_e32 v90, 16, v91
	v_and_b32_e32 v91, 0xffff0000, v91
	s_cbranch_execnz .LBB0_525

; #define GAS __attribute__((address_space(1)))
;     __device__ __forceinline__ void operator()(const pg8::f32x4 (&acc)[2][2][4][2], const pg8::Unit& u, int wr, int wc, int fr, int fq) const {
;     ...
;                 for (int bj = 0; bj < 2; ++bj) { const size_t o = off + bj * 128; pg8::f32x4 b0, b1;
;                     if (first) { b0 = *(const GAS pg8::f32x4*)(base32 + o); b1 = *(const GAS pg8::f32x4*)(base32 + o + 4); }
;                     else { const v4u w = *(const GAS v4u*)(xres + o);
;                         b0 = (pg8::f32x4){__uint_as_float(w.x << 16), __uint_as_float(w.x & 0xffff0000u), __uint_as_float(w.y << 16), __uint_as_float(w.y & 0xffff0000u)};
;                         b1 = (pg8::f32x4){__uint_as_float(w.z << 16), __uint_as_float(w.z & 0xffff0000u), __uint_as_float(w.w << 16), __uint_as_float(w.w & 0xffff0000u)}; }
.LBB0_536:
	v_or_b32_e32 v88, 48, v152
	v_ashrrev_i32_e32 v89, 31, v88
	s_waitcnt lgkmcnt(0)
	v_lshlrev_b64 v[80:81], 10, v[88:89]
	v_lshl_add_u64 v[94:95], v[80:81], 0, v[150:151]
	s_and_b64 vcc, exec, s[22:23]
	v_lshl_add_u64 v[90:91], v[94:95], 1, s[16:17]
	s_cbranch_vccz .LBB0_637
	s_waitcnt vmcnt(9)
	v_mov_b32_e32 v80, v198
	v_mov_b32_e32 v81, v199
	v_mov_b32_e32 v82, v200
	v_mov_b32_e32 v83, v201
	v_lshlrev_b32_e32 v84, 16, v80
	v_and_b32_e32 v85, 0xffff0000, v80
	v_lshlrev_b32_e32 v86, 16, v81
	v_and_b32_e32 v87, 0xffff0000, v81
	v_lshlrev_b32_e32 v80, 16, v82
	v_and_b32_e32 v81, 0xffff0000, v82
	v_lshlrev_b32_e32 v82, 16, v83
	v_and_b32_e32 v83, 0xffff0000, v83
	v_lshl_add_u64 v[92:93], v[94:95], 2, s[14:15]
	s_cbranch_execnz .LBB0_539

; #define GAS __attribute__((address_space(1)))
;     __device__ __forceinline__ void operator()(const pg8::f32x4 (&acc)[2][2][4][2], const pg8::Unit& u, int wr, int wc, int fr, int fq) const {
;     ...
;                 for (int bj = 0; bj < 2; ++bj) { const size_t o = off + bj * 128; pg8::f32x4 b0, b1;
;                     if (first) { b0 = *(const GAS pg8::f32x4*)(base32 + o); b1 = *(const GAS pg8::f32x4*)(base32 + o + 4); }
;                     else { const v4u w = *(const GAS v4u*)(xres + o);
;                         b0 = (pg8::f32x4){__uint_as_float(w.x << 16), __uint_as_float(w.x & 0xffff0000u), __uint_as_float(w.y << 16), __uint_as_float(w.y & 0xffff0000u)};
;                         b1 = (pg8::f32x4){__uint_as_float(w.z << 16), __uint_as_float(w.z & 0xffff0000u), __uint_as_float(w.w << 16), __uint_as_float(w.w & 0xffff0000u)}; }
.LBB0_542:
	s_waitcnt vmcnt(8)
	v_mov_b32_e32 v72, v202
	v_mov_b32_e32 v73, v203
	v_mov_b32_e32 v74, v204
	v_mov_b32_e32 v75, v205
	v_lshlrev_b32_e32 v76, 16, v72
	v_and_b32_e32 v77, 0xffff0000, v72
	v_lshlrev_b32_e32 v78, 16, v73
	v_and_b32_e32 v79, 0xffff0000, v73
	v_lshlrev_b32_e32 v72, 16, v74
	v_and_b32_e32 v73, 0xffff0000, v74
	v_lshlrev_b32_e32 v74, 16, v75
	v_and_b32_e32 v75, 0xffff0000, v75
	s_cbranch_execnz .LBB0_544

; #define GAS __attribute__((address_space(1)))
;     __device__ __forceinline__ void operator()(const pg8::f32x4 (&acc)[2][2][4][2], const pg8::Unit& u, int wr, int wc, int fr, int fq) const {
;     ...
;                 for (int bj = 0; bj < 2; ++bj) { const size_t o = off + bj * 128; pg8::f32x4 b0, b1;
;                     if (first) { b0 = *(const GAS pg8::f32x4*)(base32 + o); b1 = *(const GAS pg8::f32x4*)(base32 + o + 4); }
;                     else { const v4u w = *(const GAS v4u*)(xres + o);
;                         b0 = (pg8::f32x4){__uint_as_float(w.x << 16), __uint_as_float(w.x & 0xffff0000u), __uint_as_float(w.y << 16), __uint_as_float(w.y & 0xffff0000u)};
;                         b1 = (pg8::f32x4){__uint_as_float(w.z << 16), __uint_as_float(w.z & 0xffff0000u), __uint_as_float(w.w << 16), __uint_as_float(w.w & 0xffff0000u)}; }
.LBB0_555:
	v_add_u32_e32 v72, 0x80, v152
	v_ashrrev_i32_e32 v73, 31, v72
	s_waitcnt lgkmcnt(0)
	v_lshlrev_b64 v[64:65], 10, v[72:73]
	v_lshl_add_u64 v[78:79], v[64:65], 0, v[150:151]
	s_and_b64 vcc, exec, s[22:23]
	v_lshl_add_u64 v[74:75], v[78:79], 1, s[16:17]
	s_cbranch_vccz .LBB0_638
	s_waitcnt vmcnt(7)
	v_mov_b32_e32 v64, v206
	v_mov_b32_e32 v65, v207
	v_mov_b32_e32 v66, v208
	v_mov_b32_e32 v67, v209
	v_lshlrev_b32_e32 v68, 16, v64
	v_and_b32_e32 v69, 0xffff0000, v64
	v_lshlrev_b32_e32 v70, 16, v65
	v_and_b32_e32 v71, 0xffff0000, v65
	v_lshlrev_b32_e32 v64, 16, v66
	v_and_b32_e32 v65, 0xffff0000, v66
	v_lshlrev_b32_e32 v66, 16, v67
	v_and_b32_e32 v67, 0xffff0000, v67
	v_lshl_add_u64 v[76:77], v[78:79], 2, s[14:15]
	s_cbranch_execnz .LBB0_558

; #define GAS __attribute__((address_space(1)))
;     __device__ __forceinline__ void operator()(const pg8::f32x4 (&acc)[2][2][4][2], const pg8::Unit& u, int wr, int wc, int fr, int fq) const {
;     ...
;                 for (int bj = 0; bj < 2; ++bj) { const size_t o = off + bj * 128; pg8::f32x4 b0, b1;
;                     if (first) { b0 = *(const GAS pg8::f32x4*)(base32 + o); b1 = *(const GAS pg8::f32x4*)(base32 + o + 4); }
;                     else { const v4u w = *(const GAS v4u*)(xres + o);
;                         b0 = (pg8::f32x4){__uint_as_float(w.x << 16), __uint_as_float(w.x & 0xffff0000u), __uint_as_float(w.y << 16), __uint_as_float(w.y & 0xffff0000u)};
;                         b1 = (pg8::f32x4){__uint_as_float(w.z << 16), __uint_as_float(w.z & 0xffff0000u), __uint_as_float(w.w << 16), __uint_as_float(w.w & 0xffff0000u)}; }
.LBB0_561:
	s_waitcnt vmcnt(6)
	v_mov_b32_e32 v56, v210
	v_mov_b32_e32 v57, v211
	v_mov_b32_e32 v58, v212
	v_mov_b32_e32 v59, v213
	v_lshlrev_b32_e32 v60, 16, v56
	v_and_b32_e32 v61, 0xffff0000, v56
	v_lshlrev_b32_e32 v62, 16, v57
	v_and_b32_e32 v63, 0xffff0000, v57
	v_lshlrev_b32_e32 v56, 16, v58
	v_and_b32_e32 v57, 0xffff0000, v58
	v_lshlrev_b32_e32 v58, 16, v59
	v_and_b32_e32 v59, 0xffff0000, v59
	s_cbranch_execnz .LBB0_563

; #define GAS __attribute__((address_space(1)))
;     __device__ __forceinline__ void operator()(const pg8::f32x4 (&acc)[2][2][4][2], const pg8::Unit& u, int wr, int wc, int fr, int fq) const {
;     ...
;                 for (int bj = 0; bj < 2; ++bj) { const size_t o = off + bj * 128; pg8::f32x4 b0, b1;
;                     if (first) { b0 = *(const GAS pg8::f32x4*)(base32 + o); b1 = *(const GAS pg8::f32x4*)(base32 + o + 4); }
;                     else { const v4u w = *(const GAS v4u*)(xres + o);
;                         b0 = (pg8::f32x4){__uint_as_float(w.x << 16), __uint_as_float(w.x & 0xffff0000u), __uint_as_float(w.y << 16), __uint_as_float(w.y & 0xffff0000u)};
;                         b1 = (pg8::f32x4){__uint_as_float(w.z << 16), __uint_as_float(w.z & 0xffff0000u), __uint_as_float(w.w << 16), __uint_as_float(w.w & 0xffff0000u)}; }
.LBB0_574:
	v_add_u32_e32 v56, 0x90, v152
	v_ashrrev_i32_e32 v57, 31, v56
	s_waitcnt lgkmcnt(0)
	v_lshlrev_b64 v[48:49], 10, v[56:57]
	v_lshl_add_u64 v[62:63], v[48:49], 0, v[150:151]
	s_and_b64 vcc, exec, s[22:23]
	v_lshl_add_u64 v[58:59], v[62:63], 1, s[16:17]
	s_cbranch_vccz .LBB0_639
	s_waitcnt vmcnt(5)
	v_mov_b32_e32 v48, v214
	v_mov_b32_e32 v49, v215
	v_mov_b32_e32 v50, v216
	v_mov_b32_e32 v51, v217
	v_lshlrev_b32_e32 v52, 16, v48
	v_and_b32_e32 v53, 0xffff0000, v48
	v_lshlrev_b32_e32 v54, 16, v49
	v_and_b32_e32 v55, 0xffff0000, v49
	v_lshlrev_b32_e32 v48, 16, v50
	v_and_b32_e32 v49, 0xffff0000, v50
	v_lshlrev_b32_e32 v50, 16, v51
	v_and_b32_e32 v51, 0xffff0000, v51
	v_lshl_add_u64 v[60:61], v[62:63], 2, s[14:15]
	s_cbranch_execnz .LBB0_577

; #define GAS __attribute__((address_space(1)))
;     __device__ __forceinline__ void operator()(const pg8::f32x4 (&acc)[2][2][4][2], const pg8::Unit& u, int wr, int wc, int fr, int fq) const {
;     ...
;                 for (int bj = 0; bj < 2; ++bj) { const size_t o = off + bj * 128; pg8::f32x4 b0, b1;
;                     if (first) { b0 = *(const GAS pg8::f32x4*)(base32 + o); b1 = *(const GAS pg8::f32x4*)(base32 + o + 4); }
;                     else { const v4u w = *(const GAS v4u*)(xres + o);
;                         b0 = (pg8::f32x4){__uint_as_float(w.x << 16), __uint_as_float(w.x & 0xffff0000u), __uint_as_float(w.y << 16), __uint_as_float(w.y & 0xffff0000u)};
;                         b1 = (pg8::f32x4){__uint_as_float(w.z << 16), __uint_as_float(w.z & 0xffff0000u), __uint_as_float(w.w << 16), __uint_as_float(w.w & 0xffff0000u)}; }
.LBB0_580:
	s_waitcnt vmcnt(4)
	v_mov_b32_e32 v40, v218
	v_mov_b32_e32 v41, v219
	v_mov_b32_e32 v42, v220
	v_mov_b32_e32 v43, v221
	v_lshlrev_b32_e32 v44, 16, v40
	v_and_b32_e32 v45, 0xffff0000, v40
	v_lshlrev_b32_e32 v46, 16, v41
	v_and_b32_e32 v47, 0xffff0000, v41
	v_lshlrev_b32_e32 v40, 16, v42
	v_and_b32_e32 v41, 0xffff0000, v42
	v_lshlrev_b32_e32 v42, 16, v43
	v_and_b32_e32 v43, 0xffff0000, v43
	s_cbranch_execnz .LBB0_582

; #define GAS __attribute__((address_space(1)))
;     __device__ __forceinline__ void operator()(const pg8::f32x4 (&acc)[2][2][4][2], const pg8::Unit& u, int wr, int wc, int fr, int fq) const {
;     ...
;                 for (int bj = 0; bj < 2; ++bj) { const size_t o = off + bj * 128; pg8::f32x4 b0, b1;
;                     if (first) { b0 = *(const GAS pg8::f32x4*)(base32 + o); b1 = *(const GAS pg8::f32x4*)(base32 + o + 4); }
;                     else { const v4u w = *(const GAS v4u*)(xres + o);
;                         b0 = (pg8::f32x4){__uint_as_float(w.x << 16), __uint_as_float(w.x & 0xffff0000u), __uint_as_float(w.y << 16), __uint_as_float(w.y & 0xffff0000u)};
;                         b1 = (pg8::f32x4){__uint_as_float(w.z << 16), __uint_as_float(w.z & 0xffff0000u), __uint_as_float(w.w << 16), __uint_as_float(w.w & 0xffff0000u)}; }
.LBB0_593:
	v_add_u32_e32 v40, 0xa0, v152
	v_ashrrev_i32_e32 v41, 31, v40
	s_waitcnt lgkmcnt(0)
	v_lshlrev_b64 v[32:33], 10, v[40:41]
	v_lshl_add_u64 v[46:47], v[32:33], 0, v[150:151]
	s_and_b64 vcc, exec, s[22:23]
	v_lshl_add_u64 v[42:43], v[46:47], 1, s[16:17]
	s_cbranch_vccz .LBB0_640
	s_waitcnt vmcnt(3)
	v_mov_b32_e32 v32, v222
	v_mov_b32_e32 v33, v223
	v_mov_b32_e32 v34, v224
	v_mov_b32_e32 v35, v225
	v_lshlrev_b32_e32 v36, 16, v32
	v_and_b32_e32 v37, 0xffff0000, v32
	v_lshlrev_b32_e32 v38, 16, v33
	v_and_b32_e32 v39, 0xffff0000, v33
	v_lshlrev_b32_e32 v32, 16, v34
	v_and_b32_e32 v33, 0xffff0000, v34
	v_lshlrev_b32_e32 v34, 16, v35
	v_and_b32_e32 v35, 0xffff0000, v35
	v_lshl_add_u64 v[44:45], v[46:47], 2, s[14:15]
	s_cbranch_execnz .LBB0_596

; #define GAS __attribute__((address_space(1)))
;     __device__ __forceinline__ void operator()(const pg8::f32x4 (&acc)[2][2][4][2], const pg8::Unit& u, int wr, int wc, int fr, int fq) const {
;     ...
;                 for (int bj = 0; bj < 2; ++bj) { const size_t o = off + bj * 128; pg8::f32x4 b0, b1;
;                     if (first) { b0 = *(const GAS pg8::f32x4*)(base32 + o); b1 = *(const GAS pg8::f32x4*)(base32 + o + 4); }
;                     else { const v4u w = *(const GAS v4u*)(xres + o);
;                         b0 = (pg8::f32x4){__uint_as_float(w.x << 16), __uint_as_float(w.x & 0xffff0000u), __uint_as_float(w.y << 16), __uint_as_float(w.y & 0xffff0000u)};
;                         b1 = (pg8::f32x4){__uint_as_float(w.z << 16), __uint_as_float(w.z & 0xffff0000u), __uint_as_float(w.w << 16), __uint_as_float(w.w & 0xffff0000u)}; }
.LBB0_599:
	s_waitcnt vmcnt(2)
	v_mov_b32_e32 v24, v226
	v_mov_b32_e32 v25, v227
	v_mov_b32_e32 v26, v228
	v_mov_b32_e32 v27, v229
	v_lshlrev_b32_e32 v28, 16, v24
	v_and_b32_e32 v29, 0xffff0000, v24
	v_lshlrev_b32_e32 v30, 16, v25
	v_and_b32_e32 v31, 0xffff0000, v25
	v_lshlrev_b32_e32 v24, 16, v26
	v_and_b32_e32 v25, 0xffff0000, v26
	v_lshlrev_b32_e32 v26, 16, v27
	v_and_b32_e32 v27, 0xffff0000, v27
	s_cbranch_execnz .LBB0_601

; #define GAS __attribute__((address_space(1)))
;     __device__ __forceinline__ void operator()(const pg8::f32x4 (&acc)[2][2][4][2], const pg8::Unit& u, int wr, int wc, int fr, int fq) const {
;     ...
;                 for (int bj = 0; bj < 2; ++bj) { const size_t o = off + bj * 128; pg8::f32x4 b0, b1;
;                     if (first) { b0 = *(const GAS pg8::f32x4*)(base32 + o); b1 = *(const GAS pg8::f32x4*)(base32 + o + 4); }
;                     else { const v4u w = *(const GAS v4u*)(xres + o);
;                         b0 = (pg8::f32x4){__uint_as_float(w.x << 16), __uint_as_float(w.x & 0xffff0000u), __uint_as_float(w.y << 16), __uint_as_float(w.y & 0xffff0000u)};
;                         b1 = (pg8::f32x4){__uint_as_float(w.z << 16), __uint_as_float(w.z & 0xffff0000u), __uint_as_float(w.w << 16), __uint_as_float(w.w & 0xffff0000u)}; }
.LBB0_612:
	v_add_u32_e32 v24, 0xb0, v152
	v_ashrrev_i32_e32 v25, 31, v24
	s_waitcnt lgkmcnt(0)
	v_lshlrev_b64 v[16:17], 10, v[24:25]
	v_lshl_add_u64 v[30:31], v[16:17], 0, v[150:151]
	s_and_b64 vcc, exec, s[22:23]
	v_lshl_add_u64 v[26:27], v[30:31], 1, s[16:17]
	s_cbranch_vccz .LBB0_641
	s_waitcnt vmcnt(1)
	v_mov_b32_e32 v16, v230
	v_mov_b32_e32 v17, v231
	v_mov_b32_e32 v18, v232
	v_mov_b32_e32 v19, v233
	v_lshlrev_b32_e32 v20, 16, v16
	v_and_b32_e32 v21, 0xffff0000, v16
	v_lshlrev_b32_e32 v22, 16, v17
	v_and_b32_e32 v23, 0xffff0000, v17
	v_lshlrev_b32_e32 v16, 16, v18
	v_and_b32_e32 v17, 0xffff0000, v18
	v_lshlrev_b32_e32 v18, 16, v19
	v_and_b32_e32 v19, 0xffff0000, v19
	v_lshl_add_u64 v[28:29], v[30:31], 2, s[14:15]
	s_cbranch_execnz .LBB0_615

; #define GAS __attribute__((address_space(1)))
;     __device__ __forceinline__ void operator()(const pg8::f32x4 (&acc)[2][2][4][2], const pg8::Unit& u, int wr, int wc, int fr, int fq) const {
;     ...
;                 for (int bj = 0; bj < 2; ++bj) { const size_t o = off + bj * 128; pg8::f32x4 b0, b1;
;                     if (first) { b0 = *(const GAS pg8::f32x4*)(base32 + o); b1 = *(const GAS pg8::f32x4*)(base32 + o + 4); }
;                     else { const v4u w = *(const GAS v4u*)(xres + o);
;                         b0 = (pg8::f32x4){__uint_as_float(w.x << 16), __uint_as_float(w.x & 0xffff0000u), __uint_as_float(w.y << 16), __uint_as_float(w.y & 0xffff0000u)};
;                         b1 = (pg8::f32x4){__uint_as_float(w.z << 16), __uint_as_float(w.z & 0xffff0000u), __uint_as_float(w.w << 16), __uint_as_float(w.w & 0xffff0000u)}; }
.LBB0_618:
	s_waitcnt vmcnt(0)
	v_mov_b32_e32 v8, v140
	v_mov_b32_e32 v9, v141
	v_mov_b32_e32 v10, v142
	v_mov_b32_e32 v11, v143
	v_lshlrev_b32_e32 v12, 16, v8
	v_and_b32_e32 v13, 0xffff0000, v8
	v_lshlrev_b32_e32 v14, 16, v9
	v_and_b32_e32 v15, 0xffff0000, v9
	v_lshlrev_b32_e32 v8, 16, v10
	v_and_b32_e32 v9, 0xffff0000, v10
	v_lshlrev_b32_e32 v10, 16, v11
	v_and_b32_e32 v11, 0xffff0000, v11
	s_cbranch_execnz .LBB0_620
